# nsa_topk rank loop: 64-bit (value, index) keys compared with one signed 64-bit compare + add-with-carry per element (was ~8 instructions per element); nsa_cmp1 prologue gain loads in two bursts
# baseline (speedup 1.0000x reference)
; DI float bf2f(bf16_t v) { return __uint_as_float(((unsigned)v) << 16); }
; DI void load_q_norm(bf16x8 (&qf)[8], const bf16_t* qrow, int g, const float* __restrict__ gain, float scale) {
;   float ss = 0.f;
; #pragma unroll
;   for (int ks = 0; ks < 8; ++ks) { qf[ks] = *(const bf16x8*)(qrow + ks * 16 + g * 8);
; #pragma unroll
;     for (int e = 0; e < 8; ++e) { const float f = bf2f((bf16_t)qf[ks][e]); ss += f * f; } }
; DI void run_phase(const Params& p0, int ph) {
;     ...
;             if (threadIdx.x == 0) qs[0] = __hip_atomic_fetch_add(ctr, 1u, __ATOMIC_RELAXED, __HIP_MEMORY_SCOPE_AGENT);
;             __syncthreads();
;             const int q = __builtin_amdgcn_readfirstlane((int)qs[0]);
;             __syncthreads();
;             if (q >= 512) break;
;             const int bg = q & 7;
;             nsa_task(p, e, bg >> 2, bg & 3, 63 - (q >> 3));
.LBB0_205:
	s_or_b64 exec, exec, s[0:1]
	v_readlane_b32 s0, v253, 3
	s_waitcnt lgkmcnt(0)
	s_barrier
	v_mov_b32_e32 v0, s0
	ds_read_b32 v0, v0
	s_mov_b64 s[0:1], -1
	s_waitcnt lgkmcnt(0)
	s_barrier
	v_readfirstlane_b32 s2, v0
	s_cmpk_gt_i32 s2, 0x1ff
	s_cbranch_scc1 .LBB0_200
	v_mov_b32_e32 v123, v199
	s_bfe_u32 s10, s2, 0x10002
	s_and_b32 s8, s2, 3
	s_ashr_i32 s0, s2, 3
	v_writelane_b32 v254, s0, 53
	v_readfirstlane_b32 s2, v123
	s_ashr_i32 s1, s2, 6
	s_sub_i32 s4, 63, s0
	s_and_b32 s0, s1, 3
	s_lshl_b32 s3, s8, 2
	v_writelane_b32 v254, s3, 54
	s_or_b32 s0, s0, s3
	s_ashr_i32 s3, s2, 3
	s_lshl_b32 s12, s4, 6
	s_andn2_b32 s3, s3, 31
	v_and_b32_e32 v122, 31, v123
	s_add_i32 s3, s3, s12
	v_writelane_b32 v254, s4, 55
	v_or_b32_e32 v114, s3, v122
	s_lshl_b32 s5, s10, 16
	s_lshl_b32 s4, s0, 12
	v_readlane_b32 s96, v253, 10
	v_readlane_b32 s97, v253, 11
	v_writelane_b32 v254, s5, 56
	s_or_b32 s96, s4, s5
	v_ashrrev_i32_e32 v115, 31, v114
	v_lshl_add_u64 v[2:3], s[96:97], 0, v[114:115]
	v_readlane_b32 s4, v254, 29
	v_bfe_u32 v68, v123, 5, 1
	v_lshlrev_b64 v[2:3], 8, v[2:3]
	v_readlane_b32 s5, v254, 30
	v_lshlrev_b32_e32 v0, 4, v68
	s_ashr_i32 s7, s3, 4
	v_lshl_add_u64 v[2:3], s[4:5], 0, v[2:3]
	v_lshl_add_u64 v[6:7], v[2:3], 0, v[0:1]
	global_load_dwordx4 v[2:5], v[6:7], off
	global_load_dwordx4 v[18:21], v[6:7], off offset:32
	global_load_dwordx4 v[28:31], v[6:7], off offset:64
	global_load_dwordx4 v[36:39], v[6:7], off offset:96
	global_load_dwordx4 v[42:45], v[6:7], off offset:128
	global_load_dwordx4 v[50:53], v[6:7], off offset:160
	global_load_dwordx4 v[60:63], v[6:7], off offset:192
	global_load_dwordx4 v[70:73], v[6:7], off offset:224
	s_add_i32 s4, s0, 1
	v_cvt_f32_ubyte0_e32 v8, s4
	v_mul_f32_e32 v8, -0.5, v8
	v_exp_f32_e32 v8, v8
	s_cmpk_lt_i32 s7, 0xffe1
	v_writelane_b32 v254, s8, 57
	v_mul_f32_e32 v124, 0x3fb8aa3b, v8
	s_nop 0
	v_readfirstlane_b32 s4, v124
	s_waitcnt vmcnt(7)
	v_and_b32_e32 v17, 0xffff0000, v2
	v_lshlrev_b32_e32 v16, 16, v2
	s_waitcnt vmcnt(6)
	v_and_b32_e32 v9, 0xffff0000, v18
	v_lshlrev_b32_e32 v8, 16, v18
	v_mul_f32_e32 v18, v17, v17
	v_and_b32_e32 v15, 0xffff0000, v3
	v_lshlrev_b32_e32 v14, 16, v3
	v_and_b32_e32 v7, 0xffff0000, v19
	v_lshlrev_b32_e32 v6, 16, v19
	v_pk_fma_f32 v[18:19], v[16:17], v[16:17], v[18:19] op_sel_hi:[1,1,0]
	s_waitcnt vmcnt(4)
	v_and_b32_e32 v35, 0xffff0000, v36
	v_lshlrev_b32_e32 v34, 16, v36
	v_and_b32_e32 v33, 0xffff0000, v37
	v_lshlrev_b32_e32 v32, 16, v37
	s_waitcnt vmcnt(3)
	v_and_b32_e32 v37, 0xffff0000, v43
	v_mul_f32_e32 v36, v15, v15
	v_pk_fma_f32 v[18:19], v[14:15], v[14:15], v[18:19]
	v_and_b32_e32 v13, 0xffff0000, v4
	v_lshlrev_b32_e32 v12, 16, v4
	v_pk_add_f32 v[18:19], v[36:37], v[18:19] op_sel_hi:[0,1]
	v_mul_f32_e32 v40, v13, v13
	v_pk_fma_f32 v[18:19], v[12:13], v[12:13], v[18:19]
	v_and_b32_e32 v11, 0xffff0000, v5
	v_lshlrev_b32_e32 v10, 16, v5
	v_pk_add_f32 v[18:19], v[40:41], v[18:19] op_sel_hi:[0,1]
	v_and_b32_e32 v5, 0xffff0000, v20
	v_lshlrev_b32_e32 v4, 16, v20
	v_and_b32_e32 v3, 0xffff0000, v21
	v_lshlrev_b32_e32 v2, 16, v21
	v_and_b32_e32 v27, 0xffff0000, v28
	v_lshlrev_b32_e32 v26, 16, v28
	v_and_b32_e32 v25, 0xffff0000, v29
	v_lshlrev_b32_e32 v24, 16, v29
	v_and_b32_e32 v23, 0xffff0000, v30
	v_lshlrev_b32_e32 v22, 16, v30
	v_and_b32_e32 v21, 0xffff0000, v31
	v_lshlrev_b32_e32 v20, 16, v31
	v_and_b32_e32 v31, 0xffff0000, v38
	v_lshlrev_b32_e32 v30, 16, v38
	v_and_b32_e32 v29, 0xffff0000, v39
	v_lshlrev_b32_e32 v28, 16, v39
	v_and_b32_e32 v39, 0xffff0000, v42
	v_lshlrev_b32_e32 v38, 16, v42
	v_mul_f32_e32 v42, v11, v11
	v_pk_fma_f32 v[18:19], v[10:11], v[10:11], v[18:19]
	v_mul_f32_e32 v46, v9, v9
	v_pk_add_f32 v[18:19], v[42:43], v[18:19] op_sel_hi:[0,1]
	v_pk_fma_f32 v[18:19], v[8:9], v[8:9], v[18:19]
	v_mul_f32_e32 v48, v7, v7
	v_pk_add_f32 v[18:19], v[46:47], v[18:19] op_sel_hi:[0,1]
	v_pk_fma_f32 v[18:19], v[6:7], v[6:7], v[18:19]
	v_mul_f32_e32 v54, v5, v5
	v_pk_add_f32 v[18:19], v[48:49], v[18:19] op_sel_hi:[0,1]
	v_pk_fma_f32 v[18:19], v[4:5], v[4:5], v[18:19]
	v_mul_f32_e32 v56, v3, v3
	v_pk_add_f32 v[18:19], v[54:55], v[18:19] op_sel_hi:[0,1]
	v_pk_fma_f32 v[18:19], v[2:3], v[2:3], v[18:19]
	v_mul_f32_e32 v58, v27, v27
	v_pk_add_f32 v[18:19], v[56:57], v[18:19] op_sel_hi:[0,1]
	v_pk_fma_f32 v[18:19], v[26:27], v[26:27], v[18:19]
	v_mul_f32_e32 v64, v25, v25
	v_pk_add_f32 v[18:19], v[58:59], v[18:19] op_sel_hi:[0,1]
	v_pk_fma_f32 v[18:19], v[24:25], v[24:25], v[18:19]
	v_mul_f32_e32 v66, v23, v23
	v_pk_add_f32 v[18:19], v[64:65], v[18:19] op_sel_hi:[0,1]
	v_pk_fma_f32 v[18:19], v[22:23], v[22:23], v[18:19]
	v_mul_f32_e32 v74, v21, v21
	v_pk_add_f32 v[18:19], v[66:67], v[18:19] op_sel_hi:[0,1]
	v_pk_fma_f32 v[18:19], v[20:21], v[20:21], v[18:19]
	v_mul_f32_e32 v76, v35, v35
	v_pk_add_f32 v[18:19], v[74:75], v[18:19] op_sel_hi:[0,1]
	v_pk_fma_f32 v[18:19], v[34:35], v[34:35], v[18:19]
	v_mul_f32_e32 v78, v33, v33
	v_pk_add_f32 v[18:19], v[76:77], v[18:19] op_sel_hi:[0,1]
	v_pk_fma_f32 v[18:19], v[32:33], v[32:33], v[18:19]
	v_mul_f32_e32 v80, v31, v31
	v_pk_add_f32 v[18:19], v[78:79], v[18:19] op_sel_hi:[0,1]
	v_pk_fma_f32 v[18:19], v[30:31], v[30:31], v[18:19]
	v_mul_f32_e32 v82, v29, v29
	v_pk_add_f32 v[18:19], v[80:81], v[18:19] op_sel_hi:[0,1]
	v_pk_fma_f32 v[18:19], v[28:29], v[28:29], v[18:19]
	v_mul_f32_e32 v84, v39, v39
	v_pk_add_f32 v[18:19], v[82:83], v[18:19] op_sel_hi:[0,1]
	v_pk_fma_f32 v[18:19], v[38:39], v[38:39], v[18:19]
	v_lshlrev_b32_e32 v36, 16, v43
	v_pk_add_f32 v[18:19], v[84:85], v[18:19] op_sel_hi:[0,1]
	v_pk_fma_f32 v[18:19], v[36:37], v[36:37], v[18:19]
	v_mul_f32_e32 v40, v37, v37
	v_pk_add_f32 v[18:19], v[40:41], v[18:19] op_sel_hi:[0,1]
	v_and_b32_e32 v41, 0xffff0000, v44
	v_lshlrev_b32_e32 v40, 16, v44
	v_pk_fma_f32 v[18:19], v[40:41], v[40:41], v[18:19]
	v_mul_f32_e32 v42, v41, v41
	v_pk_add_f32 v[18:19], v[42:43], v[18:19] op_sel_hi:[0,1]
	v_and_b32_e32 v43, 0xffff0000, v45
	v_lshlrev_b32_e32 v42, 16, v45
	v_pk_fma_f32 v[18:19], v[42:43], v[42:43], v[18:19]
	v_mul_f32_e32 v44, v43, v43
	v_pk_add_f32 v[18:19], v[44:45], v[18:19] op_sel_hi:[0,1]
	s_waitcnt vmcnt(2)
; DI float bf2f(bf16_t v) { return __uint_as_float(((unsigned)v) << 16); }
; DI unsigned pk2(float lo, float hi) { const f32x2g f = {lo, hi}; const hwbf16x2g r = __builtin_convertvector(f, hwbf16x2g); return __builtin_bit_cast(unsigned, r); }
; DI float xhalf_sum(float v) { const auto r = __builtin_amdgcn_permlane32_swap(__float_as_uint(v), __float_as_uint(v), false, false); return __uint_as_float(r[0]) + __uint_as_float(r[1]); }
; DI void load_q_norm(bf16x8 (&qf)[8], const bf16_t* qrow, int g, const float* __restrict__ gain, float scale) {
;     ...
;   ss = xhalf_sum(ss);
;   const float rs = rsqrtf(ss * (1.f / 128.f) + EPS_) * scale;
; #pragma unroll
;   for (int ks = 0; ks < 8; ++ks) {
;     const f32x4 g0 = *(const f32x4*)(gain + ks * 16 + g * 8), g1 = *(const f32x4*)(gain + ks * 16 + g * 8 + 4);
;     u32x4 o;
;     o.x = pk2(bf2f((bf16_t)qf[ks][0]) * rs * g0[0], bf2f((bf16_t)qf[ks][1]) * rs * g0[1]);
;     o.y = pk2(bf2f((bf16_t)qf[ks][2]) * rs * g0[2], bf2f((bf16_t)qf[ks][3]) * rs * g0[3]);
;     o.z = pk2(bf2f((bf16_t)qf[ks][4]) * rs * g1[0], bf2f((bf16_t)qf[ks][5]) * rs * g1[1]);
;     o.w = pk2(bf2f((bf16_t)qf[ks][6]) * rs * g1[2], bf2f((bf16_t)qf[ks][7]) * rs * g1[3]);
;     qf[ks] = __builtin_bit_cast(bf16x8, o);
;   }
	v_and_b32_e32 v45, 0xffff0000, v50
	v_lshlrev_b32_e32 v44, 16, v50
	v_pk_fma_f32 v[18:19], v[44:45], v[44:45], v[18:19]
	v_mul_f32_e32 v46, v45, v45
	v_pk_add_f32 v[18:19], v[46:47], v[18:19] op_sel_hi:[0,1]
	v_and_b32_e32 v47, 0xffff0000, v51
	v_lshlrev_b32_e32 v46, 16, v51
	v_pk_fma_f32 v[18:19], v[46:47], v[46:47], v[18:19]
	v_mul_f32_e32 v48, v47, v47
	v_pk_add_f32 v[18:19], v[48:49], v[18:19] op_sel_hi:[0,1]
	v_and_b32_e32 v49, 0xffff0000, v52
	v_lshlrev_b32_e32 v48, 16, v52
	v_pk_fma_f32 v[18:19], v[48:49], v[48:49], v[18:19]
	v_mul_f32_e32 v50, v49, v49
	v_pk_add_f32 v[18:19], v[50:51], v[18:19] op_sel_hi:[0,1]
	v_and_b32_e32 v51, 0xffff0000, v53
	v_lshlrev_b32_e32 v50, 16, v53
	v_pk_fma_f32 v[18:19], v[50:51], v[50:51], v[18:19]
	v_mul_f32_e32 v52, v51, v51
	v_pk_add_f32 v[18:19], v[52:53], v[18:19] op_sel_hi:[0,1]
	s_waitcnt vmcnt(1)
	v_and_b32_e32 v59, 0xffff0000, v60
	v_lshlrev_b32_e32 v58, 16, v60
	v_pk_fma_f32 v[18:19], v[58:59], v[58:59], v[18:19]
	v_mul_f32_e32 v52, v59, v59
	v_pk_add_f32 v[18:19], v[52:53], v[18:19] op_sel_hi:[0,1]
	v_and_b32_e32 v53, 0xffff0000, v61
	v_lshlrev_b32_e32 v52, 16, v61
	v_pk_fma_f32 v[18:19], v[52:53], v[52:53], v[18:19]
	v_mul_f32_e32 v54, v53, v53
	v_pk_add_f32 v[18:19], v[54:55], v[18:19] op_sel_hi:[0,1]
	v_and_b32_e32 v55, 0xffff0000, v62
	v_lshlrev_b32_e32 v54, 16, v62
	v_pk_fma_f32 v[18:19], v[54:55], v[54:55], v[18:19]
	v_mul_f32_e32 v56, v55, v55
	v_pk_add_f32 v[18:19], v[56:57], v[18:19] op_sel_hi:[0,1]
	v_and_b32_e32 v57, 0xffff0000, v63
	v_lshlrev_b32_e32 v56, 16, v63
	v_pk_fma_f32 v[18:19], v[56:57], v[56:57], v[18:19]
	v_mul_f32_e32 v60, v57, v57
	v_pk_add_f32 v[18:19], v[60:61], v[18:19] op_sel_hi:[0,1]
	s_waitcnt vmcnt(0)
	v_and_b32_e32 v67, 0xffff0000, v70
	v_lshlrev_b32_e32 v66, 16, v70
	v_pk_fma_f32 v[18:19], v[66:67], v[66:67], v[18:19]
	v_mul_f32_e32 v60, v67, v67
	v_pk_add_f32 v[18:19], v[60:61], v[18:19] op_sel_hi:[0,1]
	v_and_b32_e32 v61, 0xffff0000, v71
	v_lshlrev_b32_e32 v60, 16, v71
	v_pk_fma_f32 v[18:19], v[60:61], v[60:61], v[18:19]
	v_mul_f32_e32 v62, v61, v61
	v_pk_add_f32 v[18:19], v[62:63], v[18:19] op_sel_hi:[0,1]
	v_and_b32_e32 v63, 0xffff0000, v72
	v_lshlrev_b32_e32 v62, 16, v72
	v_pk_fma_f32 v[18:19], v[62:63], v[62:63], v[18:19]
	v_mul_f32_e32 v64, v63, v63
	v_pk_add_f32 v[18:19], v[64:65], v[18:19] op_sel_hi:[0,1]
	v_and_b32_e32 v65, 0xffff0000, v73
	v_lshlrev_b32_e32 v64, 16, v73
	v_pk_fma_f32 v[18:19], v[64:65], v[64:65], v[18:19]
	v_mul_f32_e32 v70, v65, v65
	v_pk_add_f32 v[18:19], v[70:71], v[18:19] op_sel_hi:[0,1]
	v_mov_b32_e32 v69, v18
	s_nop 1
	v_permlane32_swap_b32_e32 v18, v69
	s_cbranch_scc1 .LBB0_211
	v_add_f32_e32 v18, v18, v69
	v_fmamk_f32 v18, v18, 0x3c000000, v249
	v_cmp_gt_f32_e32 vcc, s84, v18
	v_mul_f32_e32 v69, 0x4b800000, v18
	s_lshl_b32 s6, s8, 16
	v_cndmask_b32_e32 v18, v18, v69, vcc
	v_rsq_f32_e32 v18, v18
	s_lshr_b32 s8, s7, 27
	v_lshlrev_b32_e32 v19, 3, v68
	s_add_i32 s7, s7, s8
	v_mul_f32_e32 v69, 0x45800000, v18
	v_cndmask_b32_e32 v18, v18, v69, vcc
	v_mul_f32_e32 v18, 0x3e0293ee, v18
	v_readlane_b32 s8, v254, 31
	v_pk_mul_f32 v[78:79], v[18:19], v[66:67] op_sel_hi:[0,1]
	v_lshlrev_b32_e32 v66, 2, v19
	v_readlane_b32 s9, v254, 32
	s_nop 4
	global_load_dwordx4 v[186:189], v66, s[8:9] offset:464
	global_load_dwordx4 v[194:197], v66, s[8:9] offset:448
	global_load_dwordx4 v[200:203], v66, s[8:9] offset:400
	global_load_dwordx4 v[228:231], v66, s[8:9] offset:384
	global_load_dwordx4 v[232:235], v66, s[8:9] offset:336
	global_load_dwordx4 v[236:239], v66, s[8:9] offset:320
	global_load_dwordx4 v[240:243], v66, s[8:9] offset:272
	global_load_dwordx4 v[244:247], v66, s[8:9] offset:256
	v_pk_mul_f32 v[60:61], v[18:19], v[60:61] op_sel_hi:[0,1]
	v_pk_mul_f32 v[52:53], v[18:19], v[52:53] op_sel_hi:[0,1]
	v_pk_mul_f32 v[44:45], v[18:19], v[44:45] op_sel_hi:[0,1]
	v_pk_mul_f32 v[36:37], v[18:19], v[36:37] op_sel_hi:[0,1]
	v_pk_mul_f32 v[38:39], v[18:19], v[38:39] op_sel_hi:[0,1]
	v_pk_mul_f32 v[34:35], v[18:19], v[34:35] op_sel_hi:[0,1]
	v_pk_mul_f32 v[32:33], v[18:19], v[32:33] op_sel_hi:[0,1]
	v_pk_mul_f32 v[30:31], v[18:19], v[30:31] op_sel_hi:[0,1]
	v_pk_mul_f32 v[28:29], v[18:19], v[28:29] op_sel_hi:[0,1]
	v_pk_mul_f32 v[26:27], v[18:19], v[26:27] op_sel_hi:[0,1]
	v_pk_mul_f32 v[24:25], v[18:19], v[24:25] op_sel_hi:[0,1]
	v_pk_mul_f32 v[22:23], v[18:19], v[22:23] op_sel_hi:[0,1]
	v_pk_mul_f32 v[20:21], v[18:19], v[20:21] op_sel_hi:[0,1]
	v_pk_mul_f32 v[8:9], v[18:19], v[8:9] op_sel_hi:[0,1]
	v_pk_mul_f32 v[6:7], v[18:19], v[6:7] op_sel_hi:[0,1]
	v_pk_mul_f32 v[4:5], v[18:19], v[4:5] op_sel_hi:[0,1]
	v_pk_mul_f32 v[2:3], v[18:19], v[2:3] op_sel_hi:[0,1]
	v_pk_mul_f32 v[16:17], v[18:19], v[16:17] op_sel_hi:[0,1]
	s_lshl_b32 s5, s10, 18
	s_ashr_i32 s7, s7, 5
	v_cvt_f32_i32_e32 v125, v114
	s_or_b32 s96, s5, s6
	v_mov_b32_e32 v128, 0
	s_addk_i32 s3, 0xfe00
	v_mov_b32_e32 v127, 0xff800000
	s_waitcnt vmcnt(6)
	v_pk_mul_f32 v[60:61], v[60:61], v[196:197]
	s_nop 0
	v_cvt_pk_bf16_f32 v83, v60, v61
	v_pk_mul_f32 v[60:61], v[18:19], v[62:63] op_sel_hi:[0,1]
	v_pk_mul_f32 v[60:61], v[60:61], v[186:187]
	v_pk_mul_f32 v[70:71], v[18:19], v[58:59] op_sel_hi:[0,1]
	v_cvt_pk_bf16_f32 v84, v60, v61
	v_pk_mul_f32 v[60:61], v[18:19], v[64:65] op_sel_hi:[0,1]
	v_pk_mul_f32 v[60:61], v[60:61], v[188:189]
	v_pk_mul_f32 v[74:75], v[78:79], v[194:195]
	v_cvt_pk_bf16_f32 v85, v60, v61
	v_cvt_pk_bf16_f32 v82, v74, v75
	s_waitcnt vmcnt(4)
; DI float bf2f(bf16_t v) { return __uint_as_float(((unsigned)v) << 16); }
; DI unsigned pk2(float lo, float hi) { const f32x2g f = {lo, hi}; const hwbf16x2g r = __builtin_convertvector(f, hwbf16x2g); return __builtin_bit_cast(unsigned, r); }
; DI void load_q_norm(bf16x8 (&qf)[8], const bf16_t* qrow, int g, const float* __restrict__ gain, float scale) {
;     ...
; #pragma unroll
;   for (int ks = 0; ks < 8; ++ks) {
;     const f32x4 g0 = *(const f32x4*)(gain + ks * 16 + g * 8), g1 = *(const f32x4*)(gain + ks * 16 + g * 8 + 4);
;     u32x4 o;
;     o.x = pk2(bf2f((bf16_t)qf[ks][0]) * rs * g0[0], bf2f((bf16_t)qf[ks][1]) * rs * g0[1]);
;     o.y = pk2(bf2f((bf16_t)qf[ks][2]) * rs * g0[2], bf2f((bf16_t)qf[ks][3]) * rs * g0[3]);
;     o.z = pk2(bf2f((bf16_t)qf[ks][4]) * rs * g1[0], bf2f((bf16_t)qf[ks][5]) * rs * g1[1]);
;     o.w = pk2(bf2f((bf16_t)qf[ks][6]) * rs * g1[2], bf2f((bf16_t)qf[ks][7]) * rs * g1[3]);
;     qf[ks] = __builtin_bit_cast(bf16x8, o);
;   }
	v_pk_mul_f32 v[52:53], v[52:53], v[230:231]
	s_nop 0
	v_cvt_pk_bf16_f32 v87, v52, v53
	v_pk_mul_f32 v[52:53], v[18:19], v[54:55] op_sel_hi:[0,1]
	v_pk_mul_f32 v[52:53], v[52:53], v[200:201]
	v_pk_mul_f32 v[62:63], v[70:71], v[228:229]
	v_cvt_pk_bf16_f32 v88, v52, v53
	v_pk_mul_f32 v[52:53], v[18:19], v[56:57] op_sel_hi:[0,1]
	v_pk_mul_f32 v[52:53], v[52:53], v[202:203]
	v_cvt_pk_bf16_f32 v86, v62, v63
	v_cvt_pk_bf16_f32 v89, v52, v53
	v_mov_b32_e32 v60, v128
	v_mov_b32_e32 v61, v128
	v_mov_b32_e32 v62, v128
	v_mov_b32_e32 v63, v128
	v_mov_b32_e32 v64, v128
	v_mov_b32_e32 v65, v128
	s_waitcnt vmcnt(2)
	v_pk_mul_f32 v[44:45], v[44:45], v[236:237]
	s_nop 0
	v_cvt_pk_bf16_f32 v90, v44, v45
	v_pk_mul_f32 v[44:45], v[18:19], v[46:47] op_sel_hi:[0,1]
	v_pk_mul_f32 v[44:45], v[44:45], v[238:239]
	v_mov_b32_e32 v56, v128
	v_cvt_pk_bf16_f32 v91, v44, v45
	v_pk_mul_f32 v[44:45], v[18:19], v[48:49] op_sel_hi:[0,1]
	v_pk_mul_f32 v[44:45], v[44:45], v[232:233]
	v_mov_b32_e32 v52, v128
	v_cvt_pk_bf16_f32 v92, v44, v45
	v_pk_mul_f32 v[44:45], v[18:19], v[50:51] op_sel_hi:[0,1]
	v_pk_mul_f32 v[44:45], v[44:45], v[234:235]
	v_mov_b32_e32 v53, v128
	v_cvt_pk_bf16_f32 v93, v44, v45
	v_mov_b32_e32 v54, v128
	v_mov_b32_e32 v55, v128
	v_mov_b32_e32 v57, v128
	v_mov_b32_e32 v58, v128
	v_mov_b32_e32 v59, v128
	s_waitcnt vmcnt(0)
	v_pk_mul_f32 v[36:37], v[36:37], v[246:247]
	s_nop 0
	v_cvt_pk_bf16_f32 v95, v36, v37
	v_pk_mul_f32 v[36:37], v[18:19], v[40:41] op_sel_hi:[0,1]
	v_pk_mul_f32 v[36:37], v[36:37], v[240:241]
	v_pk_mul_f32 v[38:39], v[38:39], v[244:245]
	v_cvt_pk_bf16_f32 v96, v36, v37
	v_pk_mul_f32 v[36:37], v[18:19], v[42:43] op_sel_hi:[0,1]
	v_pk_mul_f32 v[36:37], v[36:37], v[242:243]
	v_cvt_pk_bf16_f32 v94, v38, v39
	v_cvt_pk_bf16_f32 v97, v36, v37
	global_load_dwordx4 v[186:189], v66, s[8:9] offset:208
	global_load_dwordx4 v[194:197], v66, s[8:9] offset:192
	global_load_dwordx4 v[200:203], v66, s[8:9] offset:144
	global_load_dwordx4 v[228:231], v66, s[8:9] offset:128
	global_load_dwordx4 v[232:235], v66, s[8:9] offset:80
	global_load_dwordx4 v[236:239], v66, s[8:9] offset:64
	global_load_dwordx4 v[240:243], v66, s[8:9] offset:16
	global_load_dwordx4 v[244:247], v66, s[8:9]
	v_mov_b32_e32 v50, 0
	v_mov_b32_e32 v51, v128
	v_mov_b32_e32 v44, v128
	v_mov_b32_e32 v45, v128
	v_mov_b32_e32 v46, v128
	v_mov_b32_e32 v47, v128
	v_mov_b32_e32 v48, v128
	v_mov_b32_e32 v49, v128
	s_waitcnt vmcnt(7)
	v_pk_mul_f32 v[30:31], v[30:31], v[186:187]
	s_waitcnt vmcnt(6)
	v_pk_mul_f32 v[34:35], v[34:35], v[194:195]
	v_pk_mul_f32 v[32:33], v[32:33], v[196:197]
	v_pk_mul_f32 v[28:29], v[28:29], v[188:189]
	v_cvt_pk_bf16_f32 v98, v34, v35
	v_cvt_pk_bf16_f32 v99, v32, v33
	v_cvt_pk_bf16_f32 v100, v30, v31
	v_cvt_pk_bf16_f32 v101, v28, v29
	v_mov_b32_e32 v36, v128
	v_mov_b32_e32 v37, v128
	v_mov_b32_e32 v38, v128
	v_mov_b32_e32 v39, v128
	v_mov_b32_e32 v40, v128
	v_mov_b32_e32 v41, v128
	v_mov_b32_e32 v42, v128
	v_mov_b32_e32 v43, v128
	s_waitcnt vmcnt(5)
	v_pk_mul_f32 v[22:23], v[22:23], v[200:201]
	s_waitcnt vmcnt(4)
	v_pk_mul_f32 v[26:27], v[26:27], v[228:229]
	v_pk_mul_f32 v[24:25], v[24:25], v[230:231]
	v_pk_mul_f32 v[20:21], v[20:21], v[202:203]
	v_cvt_pk_bf16_f32 v102, v26, v27
	v_cvt_pk_bf16_f32 v103, v24, v25
	v_cvt_pk_bf16_f32 v104, v22, v23
	v_cvt_pk_bf16_f32 v105, v20, v21
	v_mov_b32_e32 v34, 0
	v_mov_b32_e32 v35, v128
	v_mov_b32_e32 v28, v128
	v_mov_b32_e32 v29, v128
	v_mov_b32_e32 v30, v128
	v_mov_b32_e32 v31, v128
	v_mov_b32_e32 v32, v128
	v_mov_b32_e32 v33, v128
	s_waitcnt vmcnt(3)
	v_pk_mul_f32 v[4:5], v[4:5], v[232:233]
	s_waitcnt vmcnt(2)
	v_pk_mul_f32 v[8:9], v[8:9], v[236:237]
	v_pk_mul_f32 v[6:7], v[6:7], v[238:239]
	v_pk_mul_f32 v[2:3], v[2:3], v[234:235]
	v_cvt_pk_bf16_f32 v106, v8, v9
	v_cvt_pk_bf16_f32 v107, v6, v7
	v_cvt_pk_bf16_f32 v108, v4, v5
	v_cvt_pk_bf16_f32 v109, v2, v3
	v_mov_b32_e32 v20, v128
	v_mov_b32_e32 v21, v128
	v_mov_b32_e32 v22, v128
	v_mov_b32_e32 v23, v128
	v_mov_b32_e32 v24, v128
	v_mov_b32_e32 v25, v128
	v_mov_b32_e32 v26, v128
	v_mov_b32_e32 v27, v128
	s_waitcnt vmcnt(0)
	v_pk_mul_f32 v[6:7], v[16:17], v[244:245]
	s_nop 0
	v_cvt_pk_bf16_f32 v110, v6, v7
	v_pk_mul_f32 v[6:7], v[18:19], v[14:15] op_sel_hi:[0,1]
	v_pk_mul_f32 v[6:7], v[6:7], v[246:247]
	v_mov_b32_e32 v8, v128
	v_cvt_pk_bf16_f32 v111, v6, v7
	v_pk_mul_f32 v[6:7], v[18:19], v[12:13] op_sel_hi:[0,1]
	v_pk_mul_f32 v[2:3], v[6:7], v[240:241]
	v_mov_b32_e32 v7, v128
	v_cvt_pk_bf16_f32 v112, v2, v3
	v_pk_mul_f32 v[2:3], v[18:19], v[10:11] op_sel_hi:[0,1]
	v_pk_mul_f32 v[2:3], v[2:3], v[242:243]
	v_mov_b32_e32 v18, 0
	v_cvt_pk_bf16_f32 v113, v2, v3
	v_div_scale_f32 v2, s[8:9], s4, s4, v192
	v_rcp_f32_e32 v3, v2
	s_mov_b32 s8, 0x43480000
	v_mov_b32_e32 v9, v128
	v_mov_b32_e32 v10, v128
	v_fma_f32 v4, -v2, v3, 1.0
	v_fmac_f32_e32 v3, v4, v3
	v_mov_b32_e32 v4, s4
	v_div_scale_f32 v4, vcc, s8, v4, s8
	v_mul_f32_e32 v5, v4, v3
	v_fma_f32 v6, -v2, v5, v4
	v_fmac_f32_e32 v5, v6, v3
	v_fma_f32 v2, -v2, v5, v4
	v_div_fmas_f32 v2, v2, v3, v5
	v_div_fixup_f32 v2, v2, s4, v192
	v_cvt_i32_f32_e32 v2, v2
	s_add_i32 s4, s7, 1
	v_readlane_b32 s6, v253, 48
	v_readlane_b32 s7, v253, 49
	v_add_u32_e32 v126, 33, v2
	v_lshl_or_b32 v2, v122, 6, v19
	v_mov_b32_e32 v3, v1
	v_or_b32_e32 v4, 32, v2
	v_mov_b32_e32 v5, v1
	v_lshl_add_u64 v[118:119], s[6:7], 0, v[2:3]
	v_lshl_or_b32 v2, v122, 8, v0
	v_mov_b32_e32 v0, 0x1cf
	s_mov_b64 s[8:9], s[96:97]
	v_lshl_add_u64 v[116:117], s[6:7], 0, v[4:5]
	v_lshl_add_u64 v[120:121], s[6:7], 0, v[2:3]
	v_lshl_add_u32 v0, v68, 6, v0
	v_mov_b32_e32 v19, v128
	v_mov_b32_e32 v2, 0
	v_mov_b32_e32 v3, v128
	v_mov_b32_e32 v4, v128
	v_mov_b32_e32 v5, v128
	v_mov_b32_e32 v6, v128
	v_mov_b32_e32 v11, v128
	v_mov_b32_e32 v12, v128
	v_mov_b32_e32 v13, v128
	v_mov_b32_e32 v14, v128
	v_mov_b32_e32 v15, v128
	v_mov_b32_e32 v16, v128
	v_mov_b32_e32 v17, v128
	s_branch .LBB0_209

; #define NEG_INF (-__builtin_inff())
; #define LAS __attribute__((address_space(3)))
; DI void nsa_topk(const Params& p, const NsaCtx c) {
;     ...
;     for (int d = -1; d <= 3; ++d) { const int n = 4 * lane + d; if (n >= 0 && n <= 254) imp += pr[n]; }
;     if (64 * lane > t) imp = NEG_INF;
;     if (lane == (t >> 6) || lane == 0) imp = __builtin_inff();
;     LAS float* sbw = ml + wave * 64;
;     sbw[lane] = imp;
;     int rank = 0;
; #pragma unroll
;     for (int m4 = 0; m4 < 16; ++m4) {
;       const f32x4 v4 = *(const LAS f32x4*)(sbw + m4 * 4);
; #pragma unroll
;       for (int e2 = 0; e2 < 4; ++e2) { const int mm = m4 * 4 + e2; rank += (v4[e2] > imp || (v4[e2] == imp && mm < lane)) ? 1 : 0; }
;     }
.LBB0_229:
	s_or_b64 exec, exec, s[2:3]
	s_add_i32 s2, s79, s33
	v_cmp_ge_i32_e32 vcc, s2, v0
	v_readlane_b32 s2, v253, 56
	v_readlane_b32 s3, v253, 57
	v_cndmask_b32_e32 v2, v248, v3, vcc
	v_mov_b32_e32 v3, 0x7f800000
	v_cndmask_b32_e64 v8, v2, v3, s[2:3]
	v_mov_b32_e32 v9, s78
	v_mbcnt_lo_u32_b32 v10, -1, 0
	v_mbcnt_hi_u32_b32 v10, -1, v10
	v_and_b32_e32 v20, 31, v10
	v_lshl_add_u32 v20, v20, 3, v9
	v_sub_u32_e32 v10, 63, v10
	v_mov_b32_e32 v11, v8
	v_mov_b32_e32 v21, 0
	s_mov_b64 s[2:3], exec
	s_mov_b32 exec_lo, -1
	s_mov_b32 exec_hi, 0
	ds_write_b64 v20, v[10:11]
	s_mov_b64 exec, s[2:3]
	ds_read_b128 v[12:15], v9
	ds_read_b128 v[16:19], v9 offset:16
	ds_read_b128 v[2:5], v9 offset:32
	s_waitcnt lgkmcnt(2)
	v_cmp_gt_i64_e32 vcc, v[12:13], v[10:11]
	v_cmp_gt_i64_e64 s[82:83], v[14:15], v[10:11]
	ds_read_b128 v[12:15], v9 offset:48
	v_addc_co_u32_e32 v21, vcc, 0, v21, vcc
	v_addc_co_u32_e64 v21, s[82:83], 0, v21, s[82:83]
	s_waitcnt lgkmcnt(2)
	v_cmp_gt_i64_e32 vcc, v[16:17], v[10:11]
	v_cmp_gt_i64_e64 s[82:83], v[18:19], v[10:11]
	ds_read_b128 v[16:19], v9 offset:64
	v_addc_co_u32_e32 v21, vcc, 0, v21, vcc
	v_addc_co_u32_e64 v21, s[82:83], 0, v21, s[82:83]
	s_waitcnt lgkmcnt(2)
	v_cmp_gt_i64_e32 vcc, v[2:3], v[10:11]
	v_cmp_gt_i64_e64 s[82:83], v[4:5], v[10:11]
	ds_read_b128 v[2:5], v9 offset:80
	v_addc_co_u32_e32 v21, vcc, 0, v21, vcc
	v_addc_co_u32_e64 v21, s[82:83], 0, v21, s[82:83]
	s_waitcnt lgkmcnt(2)
	v_cmp_gt_i64_e32 vcc, v[12:13], v[10:11]
	v_cmp_gt_i64_e64 s[82:83], v[14:15], v[10:11]
	ds_read_b128 v[12:15], v9 offset:96
	v_addc_co_u32_e32 v21, vcc, 0, v21, vcc
	v_addc_co_u32_e64 v21, s[82:83], 0, v21, s[82:83]
	s_waitcnt lgkmcnt(2)
	v_cmp_gt_i64_e32 vcc, v[16:17], v[10:11]
	v_cmp_gt_i64_e64 s[82:83], v[18:19], v[10:11]
	ds_read_b128 v[16:19], v9 offset:112
	v_addc_co_u32_e32 v21, vcc, 0, v21, vcc
	v_addc_co_u32_e64 v21, s[82:83], 0, v21, s[82:83]
	s_waitcnt lgkmcnt(2)
	v_cmp_gt_i64_e32 vcc, v[2:3], v[10:11]
	v_cmp_gt_i64_e64 s[82:83], v[4:5], v[10:11]
	ds_read_b128 v[2:5], v9 offset:128
	v_addc_co_u32_e32 v21, vcc, 0, v21, vcc
	v_addc_co_u32_e64 v21, s[82:83], 0, v21, s[82:83]
	s_waitcnt lgkmcnt(2)
	v_cmp_gt_i64_e32 vcc, v[12:13], v[10:11]
	v_cmp_gt_i64_e64 s[82:83], v[14:15], v[10:11]
	ds_read_b128 v[12:15], v9 offset:144
	v_addc_co_u32_e32 v21, vcc, 0, v21, vcc
	v_addc_co_u32_e64 v21, s[82:83], 0, v21, s[82:83]
	s_waitcnt lgkmcnt(2)
	v_cmp_gt_i64_e32 vcc, v[16:17], v[10:11]
	v_cmp_gt_i64_e64 s[82:83], v[18:19], v[10:11]
	ds_read_b128 v[16:19], v9 offset:160
	v_addc_co_u32_e32 v21, vcc, 0, v21, vcc
	v_addc_co_u32_e64 v21, s[82:83], 0, v21, s[82:83]
	s_waitcnt lgkmcnt(2)
	v_cmp_gt_i64_e32 vcc, v[2:3], v[10:11]
	v_cmp_gt_i64_e64 s[82:83], v[4:5], v[10:11]
	ds_read_b128 v[2:5], v9 offset:176
	v_addc_co_u32_e32 v21, vcc, 0, v21, vcc
	v_addc_co_u32_e64 v21, s[82:83], 0, v21, s[82:83]
	s_waitcnt lgkmcnt(2)
	v_cmp_gt_i64_e32 vcc, v[12:13], v[10:11]
	v_cmp_gt_i64_e64 s[82:83], v[14:15], v[10:11]
	ds_read_b128 v[12:15], v9 offset:192
	v_addc_co_u32_e32 v21, vcc, 0, v21, vcc
	v_addc_co_u32_e64 v21, s[82:83], 0, v21, s[82:83]
	s_waitcnt lgkmcnt(2)
	v_cmp_gt_i64_e32 vcc, v[16:17], v[10:11]
	v_cmp_gt_i64_e64 s[82:83], v[18:19], v[10:11]
	ds_read_b128 v[16:19], v9 offset:208
	v_addc_co_u32_e32 v21, vcc, 0, v21, vcc
	v_addc_co_u32_e64 v21, s[82:83], 0, v21, s[82:83]
	s_waitcnt lgkmcnt(2)
	v_cmp_gt_i64_e32 vcc, v[2:3], v[10:11]
	v_cmp_gt_i64_e64 s[82:83], v[4:5], v[10:11]
	ds_read_b128 v[2:5], v9 offset:224
	v_addc_co_u32_e32 v21, vcc, 0, v21, vcc
	v_addc_co_u32_e64 v21, s[82:83], 0, v21, s[82:83]
	s_waitcnt lgkmcnt(2)
	v_cmp_gt_i64_e32 vcc, v[12:13], v[10:11]
	v_cmp_gt_i64_e64 s[82:83], v[14:15], v[10:11]
	ds_read_b128 v[12:15], v9 offset:240
	v_addc_co_u32_e32 v21, vcc, 0, v21, vcc
	v_addc_co_u32_e64 v21, s[82:83], 0, v21, s[82:83]
	s_waitcnt lgkmcnt(2)
	v_cmp_gt_i64_e32 vcc, v[16:17], v[10:11]
	v_cmp_gt_i64_e64 s[82:83], v[18:19], v[10:11]
	s_nop 0
	v_addc_co_u32_e32 v21, vcc, 0, v21, vcc
	v_addc_co_u32_e64 v21, s[82:83], 0, v21, s[82:83]
	s_waitcnt lgkmcnt(1)
	v_cmp_gt_i64_e32 vcc, v[2:3], v[10:11]
	v_cmp_gt_i64_e64 s[82:83], v[4:5], v[10:11]
	s_nop 0
	v_addc_co_u32_e32 v21, vcc, 0, v21, vcc
	v_addc_co_u32_e64 v21, s[82:83], 0, v21, s[82:83]
	s_waitcnt lgkmcnt(0)
; #define LAS __attribute__((address_space(3)))
; DI void nsa_topk(const Params& p, const NsaCtx c) {
;     ...
;     LAS float* sbw = ml + wave * 64;
;     sbw[lane] = imp;
;     int rank = 0;
; #pragma unroll
;     for (int m4 = 0; m4 < 16; ++m4) {
;       const f32x4 v4 = *(const LAS f32x4*)(sbw + m4 * 4);
; #pragma unroll
;       for (int e2 = 0; e2 < 4; ++e2) { const int mm = m4 * 4 + e2; rank += (v4[e2] > imp || (v4[e2] == imp && mm < lane)) ? 1 : 0; }
;     }
;     const unsigned long long msk = __ballot(rank < 16);
;     if (lane == 0) sel[sub * 32 + row] = msk;
	v_cmp_gt_i64_e32 vcc, v[12:13], v[10:11]
	v_cmp_gt_i64_e64 s[82:83], v[14:15], v[10:11]
	s_nop 0
	v_addc_co_u32_e32 v21, vcc, 0, v21, vcc
	v_addc_co_u32_e64 v21, s[82:83], 0, v21, s[82:83]
	s_mov_b64 s[2:3], exec
	s_mov_b32 exec_lo, 0
	s_mov_b32 exec_hi, -1
	ds_write_b64 v20, v[10:11]
	s_mov_b64 exec, s[2:3]
	ds_read_b128 v[12:15], v9
	ds_read_b128 v[16:19], v9 offset:16
	ds_read_b128 v[2:5], v9 offset:32
	s_waitcnt lgkmcnt(2)
	v_cmp_gt_i64_e32 vcc, v[12:13], v[10:11]
	v_cmp_gt_i64_e64 s[82:83], v[14:15], v[10:11]
	ds_read_b128 v[12:15], v9 offset:48
	v_addc_co_u32_e32 v21, vcc, 0, v21, vcc
	v_addc_co_u32_e64 v21, s[82:83], 0, v21, s[82:83]
	s_waitcnt lgkmcnt(2)
	v_cmp_gt_i64_e32 vcc, v[16:17], v[10:11]
	v_cmp_gt_i64_e64 s[82:83], v[18:19], v[10:11]
	ds_read_b128 v[16:19], v9 offset:64
	v_addc_co_u32_e32 v21, vcc, 0, v21, vcc
	v_addc_co_u32_e64 v21, s[82:83], 0, v21, s[82:83]
	s_waitcnt lgkmcnt(2)
	v_cmp_gt_i64_e32 vcc, v[2:3], v[10:11]
	v_cmp_gt_i64_e64 s[82:83], v[4:5], v[10:11]
	ds_read_b128 v[2:5], v9 offset:80
	v_addc_co_u32_e32 v21, vcc, 0, v21, vcc
	v_addc_co_u32_e64 v21, s[82:83], 0, v21, s[82:83]
	s_waitcnt lgkmcnt(2)
	v_cmp_gt_i64_e32 vcc, v[12:13], v[10:11]
	v_cmp_gt_i64_e64 s[82:83], v[14:15], v[10:11]
	ds_read_b128 v[12:15], v9 offset:96
	v_addc_co_u32_e32 v21, vcc, 0, v21, vcc
	v_addc_co_u32_e64 v21, s[82:83], 0, v21, s[82:83]
	s_waitcnt lgkmcnt(2)
	v_cmp_gt_i64_e32 vcc, v[16:17], v[10:11]
	v_cmp_gt_i64_e64 s[82:83], v[18:19], v[10:11]
	ds_read_b128 v[16:19], v9 offset:112
	v_addc_co_u32_e32 v21, vcc, 0, v21, vcc
	v_addc_co_u32_e64 v21, s[82:83], 0, v21, s[82:83]
	s_waitcnt lgkmcnt(2)
	v_cmp_gt_i64_e32 vcc, v[2:3], v[10:11]
	v_cmp_gt_i64_e64 s[82:83], v[4:5], v[10:11]
	ds_read_b128 v[2:5], v9 offset:128
	v_addc_co_u32_e32 v21, vcc, 0, v21, vcc
	v_addc_co_u32_e64 v21, s[82:83], 0, v21, s[82:83]
	s_waitcnt lgkmcnt(2)
	v_cmp_gt_i64_e32 vcc, v[12:13], v[10:11]
	v_cmp_gt_i64_e64 s[82:83], v[14:15], v[10:11]
	ds_read_b128 v[12:15], v9 offset:144
	v_addc_co_u32_e32 v21, vcc, 0, v21, vcc
	v_addc_co_u32_e64 v21, s[82:83], 0, v21, s[82:83]
	s_waitcnt lgkmcnt(2)
	v_cmp_gt_i64_e32 vcc, v[16:17], v[10:11]
	v_cmp_gt_i64_e64 s[82:83], v[18:19], v[10:11]
	ds_read_b128 v[16:19], v9 offset:160
	v_addc_co_u32_e32 v21, vcc, 0, v21, vcc
	v_addc_co_u32_e64 v21, s[82:83], 0, v21, s[82:83]
	s_waitcnt lgkmcnt(2)
	v_cmp_gt_i64_e32 vcc, v[2:3], v[10:11]
	v_cmp_gt_i64_e64 s[82:83], v[4:5], v[10:11]
	ds_read_b128 v[2:5], v9 offset:176
	v_addc_co_u32_e32 v21, vcc, 0, v21, vcc
	v_addc_co_u32_e64 v21, s[82:83], 0, v21, s[82:83]
	s_waitcnt lgkmcnt(2)
	v_cmp_gt_i64_e32 vcc, v[12:13], v[10:11]
	v_cmp_gt_i64_e64 s[82:83], v[14:15], v[10:11]
	ds_read_b128 v[12:15], v9 offset:192
	v_addc_co_u32_e32 v21, vcc, 0, v21, vcc
	v_addc_co_u32_e64 v21, s[82:83], 0, v21, s[82:83]
	s_waitcnt lgkmcnt(2)
	v_cmp_gt_i64_e32 vcc, v[16:17], v[10:11]
	v_cmp_gt_i64_e64 s[82:83], v[18:19], v[10:11]
	ds_read_b128 v[16:19], v9 offset:208
	v_addc_co_u32_e32 v21, vcc, 0, v21, vcc
	v_addc_co_u32_e64 v21, s[82:83], 0, v21, s[82:83]
	s_waitcnt lgkmcnt(2)
	v_cmp_gt_i64_e32 vcc, v[2:3], v[10:11]
	v_cmp_gt_i64_e64 s[82:83], v[4:5], v[10:11]
	ds_read_b128 v[2:5], v9 offset:224
	v_addc_co_u32_e32 v21, vcc, 0, v21, vcc
	v_addc_co_u32_e64 v21, s[82:83], 0, v21, s[82:83]
	s_waitcnt lgkmcnt(2)
	v_cmp_gt_i64_e32 vcc, v[12:13], v[10:11]
	v_cmp_gt_i64_e64 s[82:83], v[14:15], v[10:11]
	ds_read_b128 v[12:15], v9 offset:240
	v_addc_co_u32_e32 v21, vcc, 0, v21, vcc
	v_addc_co_u32_e64 v21, s[82:83], 0, v21, s[82:83]
	s_waitcnt lgkmcnt(2)
	v_cmp_gt_i64_e32 vcc, v[16:17], v[10:11]
	v_cmp_gt_i64_e64 s[82:83], v[18:19], v[10:11]
	s_nop 0
	v_addc_co_u32_e32 v21, vcc, 0, v21, vcc
	v_addc_co_u32_e64 v21, s[82:83], 0, v21, s[82:83]
	s_waitcnt lgkmcnt(1)
	v_cmp_gt_i64_e32 vcc, v[2:3], v[10:11]
	v_cmp_gt_i64_e64 s[82:83], v[4:5], v[10:11]
	s_nop 0
	v_addc_co_u32_e32 v21, vcc, 0, v21, vcc
	v_addc_co_u32_e64 v21, s[82:83], 0, v21, s[82:83]
	s_waitcnt lgkmcnt(0)
	v_cmp_gt_i64_e32 vcc, v[12:13], v[10:11]
	v_cmp_gt_i64_e64 s[82:83], v[14:15], v[10:11]
	s_nop 0
	v_addc_co_u32_e32 v21, vcc, 0, v21, vcc
	v_addc_co_u32_e64 v21, s[82:83], 0, v21, s[82:83]
	v_cmp_gt_u32_e32 vcc, 16, v21
	s_and_saveexec_b64 s[2:3], s[24:25]
	s_cbranch_execz .LBB0_224
	s_add_i32 s81, s80, 0
	v_mov_b32_e32 v2, s81
	s_movk_i32 s81, 0x2000
	v_mov_b64_e32 v[4:5], vcc
	ds_write_b64 v2, v[4:5]
	s_branch .LBB0_224
